# strategy 7.4 on the attention loop: one static s_setprio 1 for waves 0-3 over the item loop (two symmetric waves per SIMD), reset at loop exit
# baseline (speedup 1.0000x reference)
; __device__ __forceinline__ void phase_attn(const h16* Pda, h16* ob, float* lse, int pat, unsigned char* ldsb) {
;     ...
;     const int lane = tid & 63, w = __builtin_amdgcn_readfirstlane(tid >> 6), fr = lane & 15, g = lane >> 4;
;     const int r = (pat == 0) ? 1 : (pat == 1 ? 4 : 16);
;     const int nbk2 = 16 / r;
;     h16* Ks = (h16*)ldsb;
;     h16* Vs = Ks + 384 * 72;
;     h16* Qs = Vs + 384 * 72;
;     h16x8 pk[6], pv[6], pq[4];
;     ...
;     const int G_ = (int)gridDim.x;
;     if (bid < 1536) ATT_LOAD(bid);
;     for (int item = bid; item < 1536; item += G_) {
;         {
;         {
;         const int mitem = ATT_MAP(item);
;         const int b = mitem / 192, rem = mitem % 192, h = rem / 16, rest = rem % 16;
;         const int p = rest / nbk2, nbA = 2 * (rest % nbk2);
; #pragma unroll
;         for (int it = 0; it < 6; ++it) {
;             const int c = tid + 512 * it, j = c >> 3, part = c & 7;
;             *(h16x8*)(Ks + j * 72 + part * 8) = pk[it];
;             *(h16x8*)(Vs + j * 72 + part * 8) = pv[it];
;         }
; #pragma unroll
;         for (int it = 0; it < 4; ++it) {
;             const int c = tid + 512 * it, i = c >> 3, part = c & 7;
;             *(h16x8*)(Qs + i * 72 + part * 8) = pq[it] * (h16)0.18033688f;
;         }
;         LDS_BARRIER();
;         if (item + G_ < 1536) ATT_LOAD(item + G_);
; #pragma unroll
;         for (int qb = 0; qb < 2; ++qb) {
;         const int nb = nbA + qb;
;         const h16* Kb = Ks + 128 * qb * 72; const h16* Vb = Vs + 128 * qb * 72; const h16* Qb = Qs + 128 * qb * 72;
;         float lp_pre = 0.f; h16x4 prev_pre[4];
; #pragma unroll
;         for (int dt = 0; dt < 4; ++dt) prev_pre[dt] = (h16x4){0, 0, 0, 0};
;         if (pat > 0) {
;             const unsigned tok_ = (unsigned)b * SEQ + p + r * (128 * nb + 16 * w + fr);
;             lp_pre = gld(lse + tok_ * 12 + h);
; #pragma unroll
;             for (int dt = 0; dt < 4; ++dt) prev_pre[dt] = gld((const h16x4*)(ob + tok_ * 768 + h * 64 + 4 * g + 16 * dt));
;         }
;         const float slope = __builtin_amdgcn_exp2f(-8.0f * (float)(h + 1) / 12.0f);
;         const float sr = slope * (float)r * 1.4426950408889634f;
;         h16x8 qf[2];
; #pragma unroll
;         for (int kk = 0; kk < 2; ++kk) qf[kk] = *(const h16x8*)(Qb + (16 * w + fr) * 72 + 32 * kk + 8 * g);
;         float sc[9][4];
;         float mx = -1e30f;
.LBB0_446:
	s_andn2_b64 vcc, exec, s[8:9]
	s_cbranch_vccnz .LBB0_525
	s_ashr_i32 s54, s12, 6
	s_and_b64 s[8:9], s[4:5], exec
	s_cselect_b32 s10, 4, 16
	s_and_b64 s[8:9], s[6:7], exec
	s_cselect_b32 s8, 1, s10
	s_and_b64 s[4:5], s[4:5], exec
	s_cselect_b32 s53, 2, 4
	s_and_b64 s[4:5], s[6:7], exec
	v_and_b32_e32 v34, 63, v99
	s_cselect_b32 s55, 0, s53
	s_cmp_lt_u32 s3, 2
	s_cselect_b64 s[4:5], -1, 0
	v_cmp_gt_u32_e32 vcc, 16, v34
	s_and_b64 s[26:27], s[4:5], vcc
	s_cmp_lt_i32 s54, 16
	s_cselect_b64 s[28:29], -1, 0
	s_cmp_gt_i32 s54, 7
	s_cselect_b64 s[30:31], -1, 0
	s_add_i32 s3, s54, 1
	s_cmp_lt_i32 s54, 15
	s_cselect_b64 s[92:93], -1, 0
	s_cmp_gt_i32 s54, 6
	s_cselect_b64 s[96:97], -1, 0
	s_add_i32 s18, s54, 2
	s_movk_i32 s25, 0x90
	v_lshlrev_b32_e32 v73, 2, v34
	v_lshrrev_b32_e32 v34, 3, v99
	s_cmp_lt_i32 s54, 14
	v_mul_lo_u32 v135, v34, s25
	v_add_u32_e32 v34, 0x200, v99
	s_cselect_b64 s[22:23], -1, 0
	s_cmp_gt_i32 s54, 5
	v_lshrrev_b32_e32 v34, 3, v34
	s_cselect_b64 s[20:21], -1, 0
	s_add_i32 s19, s54, 3
	v_mul_lo_u32 v137, v34, s25
	v_add_u32_e32 v34, 0x400, v99
	s_cmp_lt_i32 s54, 13
	v_and_b32_e32 v35, 15, v99
	v_lshrrev_b32_e32 v34, 3, v34
	s_cselect_b64 s[88:89], -1, 0
	s_cmp_gt_i32 s54, 4
	v_lshlrev_b32_e32 v32, 4, v99
	v_lshl_or_b32 v130, s54, 4, v35
	v_mul_lo_u32 v139, v34, s25
	v_add_u32_e32 v34, 0x600, v99
	s_cselect_b64 s[6:7], -1, 0
	s_add_i32 s24, s54, 4
	v_and_b32_e32 v69, 0x70, v32
	v_readlane_b32 s9, v254, 40
	v_mul_lo_u32 v131, v130, s25
	v_lshrrev_b32_e32 v34, 3, v34
	s_cmp_lt_i32 s54, 12
	v_add_u32_e32 v32, 0, v69
	v_add_u32_e32 v128, s9, v69
	v_cvt_f32_ubyte0_e32 v129, s8
	v_add_u32_e32 v69, s9, v131
	v_mul_lo_u32 v141, v34, s25
	v_add_u32_e32 v34, 0x800, v99
	s_cselect_b64 s[8:9], -1, 0
	s_cmp_gt_i32 s54, 3
	v_lshrrev_b32_e32 v34, 3, v34
	s_cselect_b64 s[10:11], -1, 0
	s_add_i32 s76, s54, 5
	v_mad_u64_u32 v[84:85], s[4:5], v34, s25, v[32:33]
	v_add_u32_e32 v34, 0xa00, v99
	s_cmp_lt_i32 s54, 11
	v_lshrrev_b32_e32 v34, 3, v34
	s_cselect_b64 s[12:13], -1, 0
	s_cmp_gt_i32 s54, 2
	v_lshrrev_b32_e32 v72, 2, v99
	v_mad_u64_u32 v[86:87], s[4:5], v34, s25, v[32:33]
	s_cselect_b64 s[14:15], -1, 0
	s_add_i32 s77, s54, 6
	v_and_b32_e32 v34, 12, v72
	v_readlane_b32 s4, v255, 25
	s_cmp_lt_i32 s54, 10
	v_add_u32_e32 v136, v32, v135
	v_add_u32_e32 v138, v32, v137
	v_add_u32_e32 v140, v32, v139
	v_add_u32_e32 v142, v32, v141
	v_lshlrev_b32_e32 v32, 1, v34
	v_readlane_b32 s5, v255, 26
	s_cselect_b64 s[16:17], -1, 0
	s_cmp_gt_i32 s54, 1
	v_or_b32_e32 v71, 0x80, v35
	v_lshl_add_u64 v[88:89], s[4:5], 0, v[32:33]
	v_or_b32_e32 v32, 1, v34
	s_cselect_b64 s[94:95], -1, 0
	s_add_i32 s78, s54, 7
	v_sub_u32_e32 v72, v71, v32
	v_cmp_lt_u32_e64 s[64:65], v32, v35
	v_lshl_or_b32 v32, s3, 4, v35
	s_cmp_lt_i32 s54, 9
	v_mul_lo_u32 v85, v32, s25
	v_lshl_or_b32 v32, s18, 4, v35
	s_cselect_b64 s[68:69], -1, 0
	s_cmp_gt_i32 s54, 0
	v_mul_lo_u32 v87, v32, s25
	v_lshl_or_b32 v32, s19, 4, v35
	s_cselect_b64 s[70:71], -1, 0
	s_add_i32 s79, s54, 8
	v_mul_lo_u32 v143, v32, s25
	v_lshl_or_b32 v32, s24, 4, v35
	s_cmp_lt_i32 s54, 8
	v_mul_lo_u32 v144, v32, s25
	v_lshl_or_b32 v32, s76, 4, v35
	s_cselect_b64 s[72:73], -1, 0
	s_cmp_gt_i32 s54, -1
	v_sub_u32_e32 v74, v71, v34
	v_mul_lo_u32 v145, v32, s25
	v_lshl_or_b32 v32, s77, 4, v35
	s_cselect_b64 s[56:57], -1, 0
	s_min_i32 s80, s54, 15
	v_xor_b32_e32 v133, 64, v73
	v_xor_b32_e32 v134, 0x80, v73
	v_bfe_u32 v73, v99, 2, 2
	v_cvt_f32_ubyte0_e32 v90, v74
	v_cvt_f32_ubyte0_e32 v91, v72
	v_or_b32_e32 v72, 3, v34
	v_or_b32_e32 v74, 2, v34
	v_mul_lo_u32 v146, v32, s25
	v_lshl_or_b32 v32, s78, 4, v35
	s_min_i32 s3, s3, 15
	s_lshl_b32 s80, s80, 4
	v_cmp_lt_u32_e64 s[4:5], v34, v35
	v_cmp_lt_u32_e64 s[66:67], v74, v35
	v_cmp_lt_u32_e64 s[60:61], v72, v35
	v_mul_lo_u32 v147, v32, s25
	v_lshl_or_b32 v32, s79, 4, v35
	v_cmp_gt_u32_e64 s[62:63], v34, v35
	v_cmp_gt_u32_e64 s[58:59], v72, v35
	v_cmp_gt_u32_e64 s[48:49], v74, v35
	v_or3_b32 v35, s80, v73, v34
	s_lshl_b32 s3, s3, 4
	v_mul_lo_u32 v150, v35, s25
	v_or3_b32 v35, s3, v73, v34
	s_min_i32 s3, s18, 15
	s_min_i32 s18, s19, 15
	s_lshl_b32 s3, s3, 4
	v_mul_lo_u32 v151, v35, s25
	v_or3_b32 v35, s3, v73, v34
	s_lshl_b32 s3, s18, 4
	v_mul_lo_u32 v152, v35, s25
	v_or3_b32 v35, s3, v73, v34
	s_min_i32 s3, s24, 15
	s_min_i32 s18, s76, 15
	s_lshl_b32 s3, s3, 4
	v_mul_lo_u32 v153, v35, s25
	v_or3_b32 v35, s3, v73, v34
	s_lshl_b32 s3, s18, 4
	v_mul_lo_u32 v154, v35, s25
	v_or3_b32 v35, s3, v73, v34
	s_min_i32 s3, s77, 15
	s_min_i32 s18, s78, 15
	s_lshl_b32 s3, s3, 4
	v_mul_lo_u32 v155, v35, s25
	v_or3_b32 v35, s3, v73, v34
	s_lshl_b32 s3, s18, 4
	v_mul_lo_u32 v156, v35, s25
	v_or3_b32 v35, s3, v73, v34
	s_min_i32 s3, s79, 15
	s_min_i32 s18, s54, 6
	s_lshl_b32 s3, s3, 4
	v_mul_lo_u32 v157, v35, s25
	v_or3_b32 v35, s3, v73, v34
	s_lshl_b32 s3, s18, 4
	v_lshlrev_b32_e32 v68, 3, v99
	s_addk_i32 s3, 0x90
	v_mul_lo_u32 v148, v32, s25
	v_and_b32_e32 v32, 24, v68
	v_or3_b32 v34, s3, v73, v34
	s_add_i32 s3, 0, 0x12000
	v_add_u32_e32 v149, 0, v32
	v_add_u32_e32 v160, s3, v32
	v_cvt_f32_ubyte0_e32 v32, s75
	v_rcp_iflag_f32_e32 v32, v32
	s_sub_i32 s3, 0, s75
	v_and_b32_e32 v70, 48, v99
	v_sub_u32_e32 v75, v71, v74
	v_mul_f32_e32 v32, 0x4f7ffffe, v32
	v_cvt_u32_f32_e32 v32, v32
	v_sub_u32_e32 v71, v71, v72
	v_add_u32_e32 v132, 0, v70
	v_cvt_f32_ubyte0_e32 v93, v71
	v_readfirstlane_b32 s18, v32
	s_mul_i32 s3, s3, s18
	s_mul_hi_u32 s3, s18, s3
	v_cvt_f32_ubyte0_e32 v92, v75
	v_mul_lo_u32 v158, v35, s25
	v_mul_lo_u32 v159, v34, s25
	s_add_i32 s50, s18, s3
	v_add_u32_e32 v161, v69, v70
	v_readfirstlane_b32 s32, v192
	s_lshr_b32 s32, s32, 6
	s_cmp_lt_u32 s32, 4
	s_cbranch_scc0 .Lattn_prio
	s_setprio 1
.Lattn_prio:
	s_branch .LBB0_449
.LBB0_448:
	s_or_b64 exec, exec, s[18:19]
	s_waitcnt lgkmcnt(0)
	s_barrier
	s_and_b64 vcc, exec, s[76:77]
	s_mov_b32 s35, s3
	s_cbranch_vccnz .LBB0_525

; #define LDS_BARRIER() do { asm volatile("s_waitcnt lgkmcnt(0)" ::: "memory"); __builtin_amdgcn_s_barrier(); asm volatile("" ::: "memory"); } while (0)
; __device__ __forceinline__ void phase_attn(const h16* Pda, h16* ob, float* lse, int pat, unsigned char* ldsb) {
;     ...
;         LDS_BARRIER();
;         }
;     }
;     }
.LBB0_525:
	s_setprio 0
	s_mov_b64 s[0:1], -1
